# EpiZ ssq float atomics: removed the vmcnt(0) drain in front of each of the 8 relaxed atomics (they were serialized round trips)
# baseline (speedup 1.0000x reference)
.LBB0_512:
	ds_swizzle_b32 v129, v128 offset:swizzle(SWAP,16)
	s_and_b64 s[2:3], s[18:19], exec
	v_cmp_gt_u32_e64 s[0:1], 16, v130
	v_ashrrev_i32_e32 v181, 31, v180
	s_cselect_b32 s11, 0, 0x9000
	s_waitcnt lgkmcnt(0)
	v_add_f32_e32 v128, v128, v129
	v_mov_b32_e32 v129, v128
	s_nop 1
	v_permlane32_swap_b32_e32 v128, v129
	s_and_saveexec_b64 s[2:3], s[0:1]
	s_cbranch_execz .LBB0_514
	s_lshl_b32 s13, s11, 2
	s_add_u32 s26, s52, s13
	s_addc_u32 s27, s53, 0
	v_lshl_add_u64 v[132:133], v[180:181], 2, s[26:27]
	v_add_f32_e32 v128, v128, v129
	flat_atomic_add_f32 v[132:133], v128

.LBB0_516:
	ds_swizzle_b32 v129, v128 offset:swizzle(SWAP,16)
	s_waitcnt lgkmcnt(0)
	v_add_f32_e32 v128, v128, v129
	v_mov_b32_e32 v129, v128
	s_nop 1
	v_permlane32_swap_b32_e32 v128, v129
	s_and_saveexec_b64 s[18:19], s[0:1]
	s_cbranch_execz .LBB0_518
	s_lshl_b32 s13, s11, 2
	s_add_u32 s26, s52, s13
	s_addc_u32 s27, s53, 0
	v_lshl_add_u64 v[132:133], v[180:181], 2, s[26:27]
	v_add_f32_e32 v128, v128, v129
	flat_atomic_add_f32 v[132:133], v128 offset:64

.LBB0_520:
	ds_swizzle_b32 v129, v128 offset:swizzle(SWAP,16)
	s_waitcnt lgkmcnt(0)
	v_add_f32_e32 v128, v128, v129
	v_mov_b32_e32 v129, v128
	s_nop 1
	v_permlane32_swap_b32_e32 v128, v129
	s_and_saveexec_b64 s[18:19], s[0:1]
	s_cbranch_execz .LBB0_522
	s_lshl_b32 s13, s11, 2
	s_add_u32 s26, s52, s13
	s_addc_u32 s27, s53, 0
	v_lshl_add_u64 v[132:133], v[180:181], 2, s[26:27]
	v_add_f32_e32 v128, v128, v129
	flat_atomic_add_f32 v[132:133], v128 offset:128

.LBB0_524:
	ds_swizzle_b32 v129, v128 offset:swizzle(SWAP,16)
	s_waitcnt lgkmcnt(0)
	v_add_f32_e32 v128, v128, v129
	v_mov_b32_e32 v129, v128
	s_nop 1
	v_permlane32_swap_b32_e32 v128, v129
	s_and_saveexec_b64 s[18:19], s[0:1]
	s_cbranch_execz .LBB0_526
	s_lshl_b32 s13, s11, 2
	s_add_u32 s26, s52, s13
	s_addc_u32 s27, s53, 0
	v_lshl_add_u64 v[132:133], v[180:181], 2, s[26:27]
	v_add_f32_e32 v128, v128, v129
	flat_atomic_add_f32 v[132:133], v128 offset:192

.LBB0_528:
	ds_swizzle_b32 v129, v128 offset:swizzle(SWAP,16)
	s_waitcnt lgkmcnt(0)
	v_add_f32_e32 v128, v128, v129
	v_mov_b32_e32 v129, v128
	s_nop 1
	v_permlane32_swap_b32_e32 v128, v129
	s_and_saveexec_b64 s[18:19], s[0:1]
	s_cbranch_execz .LBB0_530
	s_lshl_b32 s13, s11, 2
	s_add_u32 s26, s52, s13
	s_addc_u32 s27, s53, 0
	v_lshl_add_u64 v[132:133], v[180:181], 2, s[26:27]
	v_add_f32_e32 v128, v128, v129
	flat_atomic_add_f32 v[132:133], v128 offset:512

.LBB0_532:
	ds_swizzle_b32 v129, v128 offset:swizzle(SWAP,16)
	s_waitcnt lgkmcnt(0)
	v_add_f32_e32 v128, v128, v129
	v_mov_b32_e32 v129, v128
	s_nop 1
	v_permlane32_swap_b32_e32 v128, v129
	s_and_saveexec_b64 s[18:19], s[0:1]
	s_cbranch_execz .LBB0_534
	s_lshl_b32 s13, s11, 2
	s_add_u32 s26, s52, s13
	s_addc_u32 s27, s53, 0
	v_lshl_add_u64 v[132:133], v[180:181], 2, s[26:27]
	v_add_f32_e32 v128, v128, v129
	flat_atomic_add_f32 v[132:133], v128 offset:576

.LBB0_536:
	ds_swizzle_b32 v129, v128 offset:swizzle(SWAP,16)
	s_waitcnt lgkmcnt(0)
	v_add_f32_e32 v128, v128, v129
	v_mov_b32_e32 v129, v128
	s_nop 1
	v_permlane32_swap_b32_e32 v128, v129
	s_and_saveexec_b64 s[18:19], s[0:1]
	s_cbranch_execz .LBB0_538
	s_lshl_b32 s13, s11, 2
	s_add_u32 s26, s52, s13
	s_addc_u32 s27, s53, 0
	v_lshl_add_u64 v[132:133], v[180:181], 2, s[26:27]
	v_add_f32_e32 v128, v128, v129
	flat_atomic_add_f32 v[132:133], v128 offset:640

.LBB0_540:
	ds_swizzle_b32 v129, v128 offset:swizzle(SWAP,16)
	s_waitcnt lgkmcnt(0)
	v_add_f32_e32 v128, v128, v129
	v_mov_b32_e32 v129, v128
	s_nop 1
	v_permlane32_swap_b32_e32 v128, v129
	s_and_saveexec_b64 s[2:3], s[0:1]
	s_cbranch_execz .LBB0_542
	s_lshl_b32 s0, s11, 2
	s_add_u32 s0, s52, s0
	s_addc_u32 s1, s53, 0
	v_lshl_add_u64 v[132:133], v[180:181], 2, s[0:1]
	v_add_f32_e32 v128, v128, v129
	flat_atomic_add_f32 v[132:133], v128 offset:704
